# GEMM main loops (gate/up, in-proj): LDS-DMA loads use scalar base + 32-bit vector offset instead of per-load 64-bit VALU adds
# baseline (speedup 1.0000x reference)
; #define PG8_STAGE(bufoff, gbase, voff) do { _Pragma("unroll") for (int _i = 0; _i < 2; ++_i) \
;         __builtin_amdgcn_global_load_lds((const unsigned*)((const char*)(gbase) + (voff)[_i]), (LAS unsigned*)(lds + (bufoff) + ldsw + _i * 8192), 16, 0, 0); } while (0)
; #define PG8_LDA(dst, b, h) do { _Pragma("unroll") for (int m = 0; m < 4; ++m) _Pragma("unroll") for (int k = 0; k < 2; ++k) dst[m][k] = *(const LAS bf16x8*)(lds + PG8_SA(b, h) + aoff + m * 2048 + k * 1024); } while (0)
; #define PG8_LDB(dst, b, h) do { _Pragma("unroll") for (int n = 0; n < 2; ++n) _Pragma("unroll") for (int k = 0; k < 2; ++k) dst[n][k] = *(const LAS bf16x8*)(lds + PG8_SB(b, h) + boff + n * 2048 + k * 1024); } while (0)
; #define PG8_MMA(ai, bj, At, Bt) do { __builtin_amdgcn_s_setprio(1); _Pragma("unroll") for (int m = 0; m < 4; ++m) _Pragma("unroll") for (int n = 0; n < 2; ++n) _Pragma("unroll") for (int k = 0; k < 2; ++k) \
;         acc[ai][bj][m][n] = __builtin_amdgcn_mfma_f32_16x16x32_bf16(Bt[n][k], At[m][k], acc[ai][bj][m][n], 0, 0, 0); __builtin_amdgcn_s_setprio(0); } while (0)
; #define PG8_WAIT_V(n) asm volatile("s_waitcnt vmcnt(" #n ")" ::: "memory")
; #define PG8_WAIT_L(n) asm volatile("s_waitcnt lgkmcnt(" #n ")" ::: "memory")
; #define PG8_BAR __builtin_amdgcn_s_barrier()
; template <class Epi, bool ALIGN_EPI, bool SP2>
; __device__ __forceinline__ void gemm_phase(LAS unsigned char* lds, const Gemm g, const Sched& S, const Epi& E) {
;     ...
;         for (int t = 0; t < nt; t += 2) {
;             const bool last = (t == nt - 2);
;             const char* a1 = cA + (size_t)(t + 1) * kstep;
;             const char* a2 = last ? nA : cA + (size_t)(t + 2) * kstep; const char* b2 = last ? nB : cB + (size_t)(t + 2) * kstep;
;             const char* a3 = a2 + kstep; const char* b3 = b2 + kstep;
;             if constexpr (SP2) {
;             PG8_LDB(B0, 0, 0); PG8_LDB(B1, 0, 1); PG8_SCHED; PG8_LDA(At, 0, 0); PG8_STAGE(PG8_SA(1, 1), a1 + hstep, voffA);
;             PG8_WAIT_V(8); PG8_WAIT_L(0); PG8_BAR; PG8_MMA(0, 0, At, B0); PG8_MMA(0, 1, At, B1); PG8_BAR; PG8_SCHED;
;             PG8_LDA(At, 0, 1); PG8_STAGE(PG8_SB(0, 0), b2, voffB); PG8_STAGE(PG8_SB(0, 1), b2 + hstep, voffB); PG8_STAGE(PG8_SA(0, 0), a2, voffA);
;             PG8_WAIT_V(8); PG8_WAIT_L(0); PG8_BAR; PG8_MMA(1, 0, At, B0); PG8_MMA(1, 1, At, B1); PG8_BAR; PG8_SCHED;
.LBB0_46:
	s_add_i32 s71, s20, 2
	s_add_u32 s2, s54, 0xfff80080
	s_addc_u32 s3, s55, -1
	s_add_i32 s76, 0, 0x10000
	s_cmp_eq_u32 s25, s20
	s_cselect_b32 s23, s13, s3
	s_cselect_b32 s22, s15, s2
	v_add_u32_e32 v151, s76, v149
	s_cselect_b32 s21, s17, s70
	s_cselect_b32 s20, s24, s69
	s_add_i32 s2, 0, 0x14000
	ds_read_b128 v[144:147], v151
	ds_read_b128 v[152:155], v151 offset:1024
	ds_read_b128 v[156:159], v151 offset:2048
	ds_read_b128 v[160:163], v151 offset:3072
	v_add_u32_e32 v151, s2, v149
	ds_read_b128 v[164:167], v151
	ds_read_b128 v[168:171], v151 offset:1024
	ds_read_b128 v[172:175], v151 offset:2048
	ds_read_b128 v[176:179], v151 offset:3072
	s_add_i32 m0, s19, 0xc000
	ds_read_b128 v[186:189], v150
	ds_read_b128 v[190:193], v150 offset:1024
	ds_read_b128 v[194:197], v150 offset:2048
	ds_read_b128 v[198:201], v150 offset:3072
	ds_read_b128 v[202:205], v150 offset:4096
	ds_read_b128 v[206:209], v150 offset:5120
	ds_read_b128 v[210:213], v150 offset:6144
	ds_read_b128 v[228:231], v150 offset:7168
	global_load_lds_dwordx4 v138, s[54:55]
	s_add_i32 m0, s19, 0xe000
	s_nop 0
	global_load_lds_dwordx4 v140, s[54:55]
	s_waitcnt vmcnt(8)
	s_waitcnt lgkmcnt(0)
	s_barrier
	s_setprio 1
	s_waitcnt lgkmcnt(0)
	v_mfma_f32_16x16x32_bf16 v[130:133], v[144:147], v[186:189], v[130:133]
	v_mfma_f32_16x16x32_bf16 v[122:125], v[156:159], v[186:189], v[122:125]
	v_mfma_f32_16x16x32_bf16 v[114:117], v[144:147], v[194:197], v[114:117]
	v_mfma_f32_16x16x32_bf16 v[106:109], v[156:159], v[194:197], v[106:109]
	v_mfma_f32_16x16x32_bf16 v[92:95], v[144:147], v[202:205], v[92:95]
	v_mfma_f32_16x16x32_bf16 v[84:87], v[156:159], v[202:205], v[84:87]
	v_mfma_f32_16x16x32_bf16 v[76:79], v[144:147], v[210:213], v[76:79]
	v_mfma_f32_16x16x32_bf16 v[68:71], v[156:159], v[210:213], v[68:71]
	v_mfma_f32_16x16x32_bf16 v[130:133], v[152:155], v[190:193], v[130:133]
	v_mfma_f32_16x16x32_bf16 v[122:125], v[160:163], v[190:193], v[122:125]
	v_mfma_f32_16x16x32_bf16 v[114:117], v[152:155], v[198:201], v[114:117]
	v_mfma_f32_16x16x32_bf16 v[106:109], v[160:163], v[198:201], v[106:109]
	v_mfma_f32_16x16x32_bf16 v[92:95], v[152:155], v[206:209], v[92:95]
	v_mfma_f32_16x16x32_bf16 v[84:87], v[160:163], v[206:209], v[84:87]
	v_mfma_f32_16x16x32_bf16 v[76:79], v[152:155], v[228:231], v[76:79]
	v_mfma_f32_16x16x32_bf16 v[68:71], v[160:163], v[228:231], v[68:71]
	s_setprio 0
	s_setprio 1
	v_mfma_f32_16x16x32_bf16 v[126:129], v[164:167], v[186:189], v[126:129]
	v_mfma_f32_16x16x32_bf16 v[118:121], v[172:175], v[186:189], v[118:121]
	v_mfma_f32_16x16x32_bf16 v[110:113], v[164:167], v[194:197], v[110:113]
	v_mfma_f32_16x16x32_bf16 v[102:105], v[172:175], v[194:197], v[102:105]
	v_mfma_f32_16x16x32_bf16 v[88:91], v[164:167], v[202:205], v[88:91]
	v_mfma_f32_16x16x32_bf16 v[80:83], v[172:175], v[202:205], v[80:83]
	v_mfma_f32_16x16x32_bf16 v[72:75], v[164:167], v[210:213], v[72:75]
	v_mfma_f32_16x16x32_bf16 v[64:67], v[172:175], v[210:213], v[64:67]
	v_mfma_f32_16x16x32_bf16 v[126:129], v[168:171], v[190:193], v[126:129]
	v_mfma_f32_16x16x32_bf16 v[118:121], v[176:179], v[190:193], v[118:121]
	v_mfma_f32_16x16x32_bf16 v[110:113], v[168:171], v[198:201], v[110:113]
	v_mfma_f32_16x16x32_bf16 v[102:105], v[176:179], v[198:201], v[102:105]
	v_mfma_f32_16x16x32_bf16 v[88:91], v[168:171], v[206:209], v[88:91]
	v_mfma_f32_16x16x32_bf16 v[80:83], v[176:179], v[206:209], v[80:83]
	v_mfma_f32_16x16x32_bf16 v[72:75], v[168:171], v[228:231], v[72:75]
	v_mfma_f32_16x16x32_bf16 v[64:67], v[176:179], v[228:231], v[64:67]
	s_setprio 0
	s_barrier
	s_add_i32 s3, s76, s57
	v_lshl_add_u64 v[180:181], s[20:21], 0, v[96:97]
	s_mov_b32 m0, s3
	ds_read_b128 v[186:189], v150 offset:16384
	ds_read_b128 v[190:193], v150 offset:17408
	ds_read_b128 v[194:197], v150 offset:18432
	ds_read_b128 v[198:201], v150 offset:19456
	ds_read_b128 v[202:205], v150 offset:20480
	ds_read_b128 v[206:209], v150 offset:21504
	ds_read_b128 v[210:213], v150 offset:22528
	ds_read_b128 v[228:231], v150 offset:23552
	global_load_lds_dwordx4 v[180:181], off
	s_add_i32 m0, s3, 0x2000
	s_add_u32 s76, s20, 0x80000
	v_lshl_add_u64 v[182:183], s[20:21], 0, v[136:137]
	s_addc_u32 s77, s21, 0
	s_add_i32 s2, s2, s57
	global_load_lds_dwordx4 v[182:183], off
	s_mov_b32 m0, s2
	v_lshl_add_u64 v[214:215], s[22:23], 0, v[134:135]
	global_load_lds_dwordx4 v96, s[76:77]
	s_add_i32 m0, s2, 0x2000
	s_nop 0
	global_load_lds_dwordx4 v136, s[76:77]
	v_lshl_add_u64 v[184:185], s[22:23], 0, v[98:99]
	s_mov_b32 m0, s19
	s_nop 0
	global_load_lds_dwordx4 v[184:185], off
	s_mov_b32 m0, s58
	s_nop 0
	global_load_lds_dwordx4 v[214:215], off
	s_waitcnt vmcnt(8)
	s_waitcnt lgkmcnt(0)
	s_barrier
; #define PG8_STAGE(bufoff, gbase, voff) do { _Pragma("unroll") for (int _i = 0; _i < 2; ++_i) \
;         __builtin_amdgcn_global_load_lds((const unsigned*)((const char*)(gbase) + (voff)[_i]), (LAS unsigned*)(lds + (bufoff) + ldsw + _i * 8192), 16, 0, 0); } while (0)
; #define PG8_LDA(dst, b, h) do { _Pragma("unroll") for (int m = 0; m < 4; ++m) _Pragma("unroll") for (int k = 0; k < 2; ++k) dst[m][k] = *(const LAS bf16x8*)(lds + PG8_SA(b, h) + aoff + m * 2048 + k * 1024); } while (0)
; #define PG8_LDB(dst, b, h) do { _Pragma("unroll") for (int n = 0; n < 2; ++n) _Pragma("unroll") for (int k = 0; k < 2; ++k) dst[n][k] = *(const LAS bf16x8*)(lds + PG8_SB(b, h) + boff + n * 2048 + k * 1024); } while (0)
; #define PG8_MMA(ai, bj, At, Bt) do { __builtin_amdgcn_s_setprio(1); _Pragma("unroll") for (int m = 0; m < 4; ++m) _Pragma("unroll") for (int n = 0; n < 2; ++n) _Pragma("unroll") for (int k = 0; k < 2; ++k) \
;         acc[ai][bj][m][n] = __builtin_amdgcn_mfma_f32_16x16x32_bf16(Bt[n][k], At[m][k], acc[ai][bj][m][n], 0, 0, 0); __builtin_amdgcn_s_setprio(0); } while (0)
; #define PG8_WAIT_V(n) asm volatile("s_waitcnt vmcnt(" #n ")" ::: "memory")
; #define PG8_WAIT_L(n) asm volatile("s_waitcnt lgkmcnt(" #n ")" ::: "memory")
; #define PG8_BAR __builtin_amdgcn_s_barrier()
; #define PG8_SCHED __builtin_amdgcn_sched_barrier(0)
; template <class Epi, bool ALIGN_EPI, bool SP2>
; __device__ __forceinline__ void gemm_phase(LAS unsigned char* lds, const Gemm g, const Sched& S, const Epi& E) {
;     ...
;             PG8_WAIT_V(8); PG8_WAIT_L(0); PG8_BAR; PG8_MMA(1, 0, At, B0); PG8_MMA(1, 1, At, B1); PG8_BAR; PG8_SCHED;
;             PG8_LDB(B0, 1, 0); PG8_LDB(B1, 1, 1); PG8_SCHED; PG8_LDA(At, 1, 0); PG8_STAGE(PG8_SA(0, 1), a2 + hstep, voffA);
;             PG8_WAIT_V(8); PG8_WAIT_L(0); PG8_BAR; PG8_MMA(0, 0, At, B0); PG8_MMA(0, 1, At, B1); PG8_BAR; PG8_SCHED;
	s_setprio 1
	s_waitcnt lgkmcnt(0)
	v_mfma_f32_16x16x32_bf16 v[60:63], v[144:147], v[186:189], v[60:63]
	v_mfma_f32_16x16x32_bf16 v[52:55], v[156:159], v[186:189], v[52:55]
	v_mfma_f32_16x16x32_bf16 v[44:47], v[144:147], v[194:197], v[44:47]
	v_mfma_f32_16x16x32_bf16 v[36:39], v[156:159], v[194:197], v[36:39]
	v_mfma_f32_16x16x32_bf16 v[28:31], v[144:147], v[202:205], v[28:31]
	v_mfma_f32_16x16x32_bf16 v[20:23], v[156:159], v[202:205], v[20:23]
	v_mfma_f32_16x16x32_bf16 v[12:15], v[144:147], v[210:213], v[12:15]
	v_mfma_f32_16x16x32_bf16 v[4:7], v[156:159], v[210:213], v[4:7]
	v_mfma_f32_16x16x32_bf16 v[60:63], v[152:155], v[190:193], v[60:63]
	v_mfma_f32_16x16x32_bf16 v[52:55], v[160:163], v[190:193], v[52:55]
	v_mfma_f32_16x16x32_bf16 v[44:47], v[152:155], v[198:201], v[44:47]
	v_mfma_f32_16x16x32_bf16 v[36:39], v[160:163], v[198:201], v[36:39]
	v_mfma_f32_16x16x32_bf16 v[28:31], v[152:155], v[206:209], v[28:31]
	v_mfma_f32_16x16x32_bf16 v[20:23], v[160:163], v[206:209], v[20:23]
	v_mfma_f32_16x16x32_bf16 v[12:15], v[152:155], v[228:231], v[12:15]
	v_mfma_f32_16x16x32_bf16 v[4:7], v[160:163], v[228:231], v[4:7]
	s_setprio 0
	s_setprio 1
	v_mfma_f32_16x16x32_bf16 v[56:59], v[164:167], v[186:189], v[56:59]
	v_mfma_f32_16x16x32_bf16 v[48:51], v[172:175], v[186:189], v[48:51]
	v_mfma_f32_16x16x32_bf16 v[40:43], v[164:167], v[194:197], v[40:43]
	v_mfma_f32_16x16x32_bf16 v[32:35], v[172:175], v[194:197], v[32:35]
	v_mfma_f32_16x16x32_bf16 v[24:27], v[164:167], v[202:205], v[24:27]
	v_mfma_f32_16x16x32_bf16 v[16:19], v[172:175], v[202:205], v[16:19]
	v_mfma_f32_16x16x32_bf16 v[8:11], v[164:167], v[210:213], v[8:11]
	v_mfma_f32_16x16x32_bf16 v[0:3], v[172:175], v[210:213], v[0:3]
	v_mfma_f32_16x16x32_bf16 v[56:59], v[168:171], v[190:193], v[56:59]
	v_mfma_f32_16x16x32_bf16 v[48:51], v[176:179], v[190:193], v[48:51]
	v_mfma_f32_16x16x32_bf16 v[40:43], v[168:171], v[198:201], v[40:43]
	v_mfma_f32_16x16x32_bf16 v[32:35], v[176:179], v[198:201], v[32:35]
	v_mfma_f32_16x16x32_bf16 v[24:27], v[168:171], v[206:209], v[24:27]
	v_mfma_f32_16x16x32_bf16 v[16:19], v[176:179], v[206:209], v[16:19]
	v_mfma_f32_16x16x32_bf16 v[8:11], v[168:171], v[228:231], v[8:11]
	v_mfma_f32_16x16x32_bf16 v[0:3], v[176:179], v[228:231], v[0:3]
	s_setprio 0
	s_barrier
	s_add_i32 s2, 0, 0x18000
	v_add_u32_e32 v151, s2, v149
	s_add_i32 s3, 0, 0x1c000
	ds_read_b128 v[144:147], v151
	ds_read_b128 v[152:155], v151 offset:1024
	ds_read_b128 v[156:159], v151 offset:2048
	ds_read_b128 v[160:163], v151 offset:3072
	v_add_u32_e32 v151, s3, v149
	ds_read_b128 v[164:167], v151
	ds_read_b128 v[168:171], v151 offset:1024
	ds_read_b128 v[172:175], v151 offset:2048
	ds_read_b128 v[176:179], v151 offset:3072
	s_add_u32 s22, s22, 0x80000
	s_addc_u32 s23, s23, 0
	s_mov_b32 m0, s59
	ds_read_b128 v[186:189], v150 offset:32768
	ds_read_b128 v[190:193], v150 offset:33792
	ds_read_b128 v[194:197], v150 offset:34816
	ds_read_b128 v[198:201], v150 offset:35840
	ds_read_b128 v[202:205], v150 offset:36864
	ds_read_b128 v[206:209], v150 offset:37888
	ds_read_b128 v[210:213], v150 offset:38912
	ds_read_b128 v[228:231], v150 offset:39936
	global_load_lds_dwordx4 v98, s[22:23]
	s_mov_b32 m0, s60
	s_nop 0
	global_load_lds_dwordx4 v134, s[22:23]
	s_waitcnt vmcnt(8)
	s_waitcnt lgkmcnt(0)
	s_barrier
	s_setprio 1
	s_waitcnt lgkmcnt(0)
	v_mfma_f32_16x16x32_bf16 v[130:133], v[144:147], v[186:189], v[130:133]
	v_mfma_f32_16x16x32_bf16 v[122:125], v[156:159], v[186:189], v[122:125]
	v_mfma_f32_16x16x32_bf16 v[114:117], v[144:147], v[194:197], v[114:117]
	v_mfma_f32_16x16x32_bf16 v[106:109], v[156:159], v[194:197], v[106:109]
	v_mfma_f32_16x16x32_bf16 v[92:95], v[144:147], v[202:205], v[92:95]
	v_mfma_f32_16x16x32_bf16 v[84:87], v[156:159], v[202:205], v[84:87]
	v_mfma_f32_16x16x32_bf16 v[76:79], v[144:147], v[210:213], v[76:79]
	v_mfma_f32_16x16x32_bf16 v[68:71], v[156:159], v[210:213], v[68:71]
	v_mfma_f32_16x16x32_bf16 v[130:133], v[152:155], v[190:193], v[130:133]
	v_mfma_f32_16x16x32_bf16 v[122:125], v[160:163], v[190:193], v[122:125]
	v_mfma_f32_16x16x32_bf16 v[114:117], v[152:155], v[198:201], v[114:117]
	v_mfma_f32_16x16x32_bf16 v[106:109], v[160:163], v[198:201], v[106:109]
	v_mfma_f32_16x16x32_bf16 v[92:95], v[152:155], v[206:209], v[92:95]
	v_mfma_f32_16x16x32_bf16 v[84:87], v[160:163], v[206:209], v[84:87]
	v_mfma_f32_16x16x32_bf16 v[76:79], v[152:155], v[228:231], v[76:79]
	v_mfma_f32_16x16x32_bf16 v[68:71], v[160:163], v[228:231], v[68:71]
	s_setprio 0
	s_setprio 1
	v_mfma_f32_16x16x32_bf16 v[126:129], v[164:167], v[186:189], v[126:129]
	v_mfma_f32_16x16x32_bf16 v[118:121], v[172:175], v[186:189], v[118:121]
	v_mfma_f32_16x16x32_bf16 v[110:113], v[164:167], v[194:197], v[110:113]
	v_mfma_f32_16x16x32_bf16 v[102:105], v[172:175], v[194:197], v[102:105]
	v_mfma_f32_16x16x32_bf16 v[88:91], v[164:167], v[202:205], v[88:91]
	v_mfma_f32_16x16x32_bf16 v[80:83], v[172:175], v[202:205], v[80:83]
	v_mfma_f32_16x16x32_bf16 v[72:75], v[164:167], v[210:213], v[72:75]
	v_mfma_f32_16x16x32_bf16 v[64:67], v[172:175], v[210:213], v[64:67]
	v_mfma_f32_16x16x32_bf16 v[126:129], v[168:171], v[190:193], v[126:129]
	v_mfma_f32_16x16x32_bf16 v[118:121], v[176:179], v[190:193], v[118:121]
	v_mfma_f32_16x16x32_bf16 v[110:113], v[168:171], v[198:201], v[110:113]
	v_mfma_f32_16x16x32_bf16 v[102:105], v[176:179], v[198:201], v[102:105]
	v_mfma_f32_16x16x32_bf16 v[88:91], v[168:171], v[206:209], v[88:91]
	v_mfma_f32_16x16x32_bf16 v[80:83], v[176:179], v[206:209], v[80:83]
	v_mfma_f32_16x16x32_bf16 v[72:75], v[168:171], v[228:231], v[72:75]
	v_mfma_f32_16x16x32_bf16 v[64:67], v[176:179], v[228:231], v[64:67]
	s_setprio 0
	s_barrier
; #define PG8_STAGE(bufoff, gbase, voff) do { _Pragma("unroll") for (int _i = 0; _i < 2; ++_i) \
;         __builtin_amdgcn_global_load_lds((const unsigned*)((const char*)(gbase) + (voff)[_i]), (LAS unsigned*)(lds + (bufoff) + ldsw + _i * 8192), 16, 0, 0); } while (0)
; #define PG8_LDA(dst, b, h) do { _Pragma("unroll") for (int m = 0; m < 4; ++m) _Pragma("unroll") for (int k = 0; k < 2; ++k) dst[m][k] = *(const LAS bf16x8*)(lds + PG8_SA(b, h) + aoff + m * 2048 + k * 1024); } while (0)
; #define PG8_MMA(ai, bj, At, Bt) do { __builtin_amdgcn_s_setprio(1); _Pragma("unroll") for (int m = 0; m < 4; ++m) _Pragma("unroll") for (int n = 0; n < 2; ++n) _Pragma("unroll") for (int k = 0; k < 2; ++k) \
;         acc[ai][bj][m][n] = __builtin_amdgcn_mfma_f32_16x16x32_bf16(Bt[n][k], At[m][k], acc[ai][bj][m][n], 0, 0, 0); __builtin_amdgcn_s_setprio(0); } while (0)
; #define PG8_WAIT_V(n) asm volatile("s_waitcnt vmcnt(" #n ")" ::: "memory")
; #define PG8_WAIT_L(n) asm volatile("s_waitcnt lgkmcnt(" #n ")" ::: "memory")
; #define PG8_BAR __builtin_amdgcn_s_barrier()
; #define PG8_SCHED __builtin_amdgcn_sched_barrier(0)
; template <class Epi, bool ALIGN_EPI, bool SP2>
; __device__ __forceinline__ void gemm_phase(LAS unsigned char* lds, const Gemm g, const Sched& S, const Epi& E) {
;     ...
;             PG8_LDA(At, 1, 1); PG8_STAGE(PG8_SB(1, 0), b3, voffB); PG8_STAGE(PG8_SB(1, 1), b3 + hstep, voffB); PG8_STAGE(PG8_SA(1, 0), a3, voffA);
;             PG8_WAIT_V(8); PG8_WAIT_L(0); PG8_BAR; PG8_MMA(1, 0, At, B0); PG8_MMA(1, 1, At, B1); PG8_BAR; PG8_SCHED;
	s_add_i32 s2, s2, s57
	v_lshl_add_u64 v[180:181], v[180:181], 0, s[94:95]
	s_mov_b32 m0, s2
	ds_read_b128 v[186:189], v150 offset:49152
	ds_read_b128 v[190:193], v150 offset:50176
	ds_read_b128 v[194:197], v150 offset:51200
	ds_read_b128 v[198:201], v150 offset:52224
	ds_read_b128 v[202:205], v150 offset:53248
	ds_read_b128 v[206:209], v150 offset:54272
	ds_read_b128 v[210:213], v150 offset:55296
	ds_read_b128 v[228:231], v150 offset:56320
	global_load_lds_dwordx4 v[180:181], off
	s_add_i32 m0, s2, 0x2000
	s_add_u32 s20, s20, 0x80080
	v_lshl_add_u64 v[180:181], v[182:183], 0, s[94:95]
	s_addc_u32 s21, s21, 0
	s_add_i32 s2, s3, s57
	global_load_lds_dwordx4 v[180:181], off
	s_mov_b32 m0, s2
	s_nop 0
	global_load_lds_dwordx4 v96, s[20:21]
	s_add_i32 m0, s2, 0x2000
	s_nop 0
	global_load_lds_dwordx4 v136, s[20:21]
	v_lshl_add_u64 v[180:181], v[184:185], 0, s[94:95]
	s_mov_b32 m0, s63
	s_nop 0
	global_load_lds_dwordx4 v[180:181], off
	v_lshl_add_u64 v[180:181], v[214:215], 0, s[94:95]
	s_mov_b32 m0, s64
	s_nop 0
	global_load_lds_dwordx4 v[180:181], off
	s_waitcnt vmcnt(8)
	s_waitcnt lgkmcnt(0)
	s_barrier
	s_setprio 1
	s_waitcnt lgkmcnt(0)
	v_mfma_f32_16x16x32_bf16 v[60:63], v[144:147], v[186:189], v[60:63]
	v_mfma_f32_16x16x32_bf16 v[52:55], v[156:159], v[186:189], v[52:55]
	v_mfma_f32_16x16x32_bf16 v[44:47], v[144:147], v[194:197], v[44:47]
	v_mfma_f32_16x16x32_bf16 v[36:39], v[156:159], v[194:197], v[36:39]
	v_mfma_f32_16x16x32_bf16 v[28:31], v[144:147], v[202:205], v[28:31]
	v_mfma_f32_16x16x32_bf16 v[20:23], v[156:159], v[202:205], v[20:23]
	v_mfma_f32_16x16x32_bf16 v[12:15], v[144:147], v[210:213], v[12:15]
	v_mfma_f32_16x16x32_bf16 v[4:7], v[156:159], v[210:213], v[4:7]
	v_mfma_f32_16x16x32_bf16 v[60:63], v[152:155], v[190:193], v[60:63]
	v_mfma_f32_16x16x32_bf16 v[52:55], v[160:163], v[190:193], v[52:55]
	v_mfma_f32_16x16x32_bf16 v[44:47], v[152:155], v[198:201], v[44:47]
	v_mfma_f32_16x16x32_bf16 v[36:39], v[160:163], v[198:201], v[36:39]
	v_mfma_f32_16x16x32_bf16 v[28:31], v[152:155], v[206:209], v[28:31]
	v_mfma_f32_16x16x32_bf16 v[20:23], v[160:163], v[206:209], v[20:23]
	v_mfma_f32_16x16x32_bf16 v[12:15], v[152:155], v[228:231], v[12:15]
	v_mfma_f32_16x16x32_bf16 v[4:7], v[160:163], v[228:231], v[4:7]
	s_setprio 0
	s_setprio 1
	v_mfma_f32_16x16x32_bf16 v[56:59], v[164:167], v[186:189], v[56:59]
	v_mfma_f32_16x16x32_bf16 v[48:51], v[172:175], v[186:189], v[48:51]
	v_mfma_f32_16x16x32_bf16 v[40:43], v[164:167], v[194:197], v[40:43]
	v_mfma_f32_16x16x32_bf16 v[32:35], v[172:175], v[194:197], v[32:35]
	v_mfma_f32_16x16x32_bf16 v[24:27], v[164:167], v[202:205], v[24:27]
	v_mfma_f32_16x16x32_bf16 v[16:19], v[172:175], v[202:205], v[16:19]
	v_mfma_f32_16x16x32_bf16 v[8:11], v[164:167], v[210:213], v[8:11]
	v_mfma_f32_16x16x32_bf16 v[0:3], v[172:175], v[210:213], v[0:3]
	v_mfma_f32_16x16x32_bf16 v[56:59], v[168:171], v[190:193], v[56:59]
	v_mfma_f32_16x16x32_bf16 v[48:51], v[176:179], v[190:193], v[48:51]
	v_mfma_f32_16x16x32_bf16 v[40:43], v[168:171], v[198:201], v[40:43]
	v_mfma_f32_16x16x32_bf16 v[32:35], v[176:179], v[198:201], v[32:35]
	v_mfma_f32_16x16x32_bf16 v[24:27], v[168:171], v[206:209], v[24:27]
	v_mfma_f32_16x16x32_bf16 v[16:19], v[176:179], v[206:209], v[16:19]
	v_mfma_f32_16x16x32_bf16 v[8:11], v[168:171], v[228:231], v[8:11]
	v_mfma_f32_16x16x32_bf16 v[0:3], v[176:179], v[228:231], v[0:3]
	s_setprio 0
	s_barrier
	s_add_u32 s54, s54, 0x100
	s_addc_u32 s55, s55, 0
	s_add_u32 s69, s69, 0x100
	s_addc_u32 s70, s70, 0
	s_cmp_ge_i32 s71, s68
	s_mov_b32 s20, s71
	s_cbranch_scc0 .LBB0_46
	v_readlane_b32 s70, v254, 48
	v_readlane_b32 s71, v254, 49
	s_and_b64 vcc, exec, s[10:11]
	s_cbranch_vccz .LBB0_49

; #define PG8_STAGE(bufoff, gbase, voff) do { _Pragma("unroll") for (int _i = 0; _i < 2; ++_i) \
;         __builtin_amdgcn_global_load_lds((const unsigned*)((const char*)(gbase) + (voff)[_i]), (LAS unsigned*)(lds + (bufoff) + ldsw + _i * 8192), 16, 0, 0); } while (0)
; #define PG8_LDA(dst, b, h) do { _Pragma("unroll") for (int m = 0; m < 4; ++m) _Pragma("unroll") for (int k = 0; k < 2; ++k) dst[m][k] = *(const LAS bf16x8*)(lds + PG8_SA(b, h) + aoff + m * 2048 + k * 1024); } while (0)
; #define PG8_LDB(dst, b, h) do { _Pragma("unroll") for (int n = 0; n < 2; ++n) _Pragma("unroll") for (int k = 0; k < 2; ++k) dst[n][k] = *(const LAS bf16x8*)(lds + PG8_SB(b, h) + boff + n * 2048 + k * 1024); } while (0)
; #define PG8_MMA(ai, bj, At, Bt) do { __builtin_amdgcn_s_setprio(1); _Pragma("unroll") for (int m = 0; m < 4; ++m) _Pragma("unroll") for (int n = 0; n < 2; ++n) _Pragma("unroll") for (int k = 0; k < 2; ++k) \
;         acc[ai][bj][m][n] = __builtin_amdgcn_mfma_f32_16x16x32_bf16(Bt[n][k], At[m][k], acc[ai][bj][m][n], 0, 0, 0); __builtin_amdgcn_s_setprio(0); } while (0)
; #define PG8_WAIT_V(n) asm volatile("s_waitcnt vmcnt(" #n ")" ::: "memory")
; #define PG8_WAIT_L(n) asm volatile("s_waitcnt lgkmcnt(" #n ")" ::: "memory")
; #define PG8_BAR __builtin_amdgcn_s_barrier()
; template <class Epi, bool ALIGN_EPI, bool SP2>
; __device__ __forceinline__ void gemm_phase(LAS unsigned char* lds, const Gemm g, const Sched& S, const Epi& E) {
;     ...
;         for (int t = 0; t < nt; t += 2) {
;             const bool last = (t == nt - 2);
;             const char* a1 = cA + (size_t)(t + 1) * kstep;
;             const char* a2 = last ? nA : cA + (size_t)(t + 2) * kstep; const char* b2 = last ? nB : cB + (size_t)(t + 2) * kstep;
;             const char* a3 = a2 + kstep; const char* b3 = b2 + kstep;
;             if constexpr (SP2) {
;             PG8_LDB(B0, 0, 0); PG8_LDB(B1, 0, 1); PG8_SCHED; PG8_LDA(At, 0, 0); PG8_STAGE(PG8_SA(1, 1), a1 + hstep, voffA);
;             PG8_WAIT_V(8); PG8_WAIT_L(0); PG8_BAR; PG8_MMA(0, 0, At, B0); PG8_MMA(0, 1, At, B1); PG8_BAR; PG8_SCHED;
;             PG8_LDA(At, 0, 1); PG8_STAGE(PG8_SB(0, 0), b2, voffB); PG8_STAGE(PG8_SB(0, 1), b2 + hstep, voffB); PG8_STAGE(PG8_SA(0, 0), a2, voffA);
;             PG8_WAIT_V(8); PG8_WAIT_L(0); PG8_BAR; PG8_MMA(1, 0, At, B0); PG8_MMA(1, 1, At, B1); PG8_BAR; PG8_SCHED;
.LBB0_585:
	s_add_i32 vcc_lo, s20, 2
	s_add_u32 s2, s44, 0xfff80080
	s_addc_u32 s3, s45, -1
	s_add_i32 vcc_hi, 0, 0x10000
	s_cmp_eq_u32 s19, s20
	s_cselect_b32 s23, s7, s3
	s_cselect_b32 s22, s9, s2
	v_add_u32_e32 v96, vcc_hi, v230
	s_cselect_b32 s21, s11, s25
	s_cselect_b32 s20, s17, s24
	s_add_i32 s91, 0, 0x14000
	ds_read_b128 v[136:139], v96
	ds_read_b128 v[140:143], v96 offset:1024
	ds_read_b128 v[144:147], v96 offset:2048
	ds_read_b128 v[148:151], v96 offset:3072
	v_add_u32_e32 v96, s91, v230
	ds_read_b128 v[152:155], v96
	ds_read_b128 v[156:159], v96 offset:1024
	ds_read_b128 v[160:163], v96 offset:2048
	ds_read_b128 v[176:179], v96 offset:3072
	s_add_i32 m0, s82, 0xc000
	ds_read_b128 v[180:183], v231
	ds_read_b128 v[186:189], v231 offset:1024
	ds_read_b128 v[190:193], v231 offset:2048
	ds_read_b128 v[194:197], v231 offset:3072
	ds_read_b128 v[198:201], v231 offset:4096
	ds_read_b128 v[202:205], v231 offset:5120
	ds_read_b128 v[206:209], v231 offset:6144
	ds_read_b128 v[210:213], v231 offset:7168
	global_load_lds_dwordx4 v172, s[44:45]
	s_add_i32 m0, s82, 0xe000
	s_nop 0
	global_load_lds_dwordx4 v174, s[44:45]
	s_waitcnt vmcnt(8)
	s_waitcnt lgkmcnt(0)
	s_barrier
	s_setprio 1
	s_waitcnt lgkmcnt(0)
	v_mfma_f32_16x16x32_bf16 v[132:135], v[136:139], v[180:183], v[132:135]
	v_mfma_f32_16x16x32_bf16 v[128:131], v[144:147], v[180:183], v[128:131]
	v_mfma_f32_16x16x32_bf16 v[116:119], v[136:139], v[190:193], v[116:119]
	v_mfma_f32_16x16x32_bf16 v[112:115], v[144:147], v[190:193], v[112:115]
	v_mfma_f32_16x16x32_bf16 v[92:95], v[136:139], v[198:201], v[92:95]
	v_mfma_f32_16x16x32_bf16 v[88:91], v[144:147], v[198:201], v[88:91]
	v_mfma_f32_16x16x32_bf16 v[76:79], v[136:139], v[206:209], v[76:79]
	v_mfma_f32_16x16x32_bf16 v[72:75], v[144:147], v[206:209], v[72:75]
	v_mfma_f32_16x16x32_bf16 v[132:135], v[140:143], v[186:189], v[132:135]
	v_mfma_f32_16x16x32_bf16 v[128:131], v[148:151], v[186:189], v[128:131]
	v_mfma_f32_16x16x32_bf16 v[116:119], v[140:143], v[194:197], v[116:119]
	v_mfma_f32_16x16x32_bf16 v[112:115], v[148:151], v[194:197], v[112:115]
	v_mfma_f32_16x16x32_bf16 v[92:95], v[140:143], v[202:205], v[92:95]
	v_mfma_f32_16x16x32_bf16 v[88:91], v[148:151], v[202:205], v[88:91]
	v_mfma_f32_16x16x32_bf16 v[76:79], v[140:143], v[210:213], v[76:79]
	v_mfma_f32_16x16x32_bf16 v[72:75], v[148:151], v[210:213], v[72:75]
	s_setprio 0
	s_setprio 1
	v_mfma_f32_16x16x32_bf16 v[124:127], v[152:155], v[180:183], v[124:127]
	v_mfma_f32_16x16x32_bf16 v[120:123], v[160:163], v[180:183], v[120:123]
	v_mfma_f32_16x16x32_bf16 v[108:111], v[152:155], v[190:193], v[108:111]
	v_mfma_f32_16x16x32_bf16 v[102:105], v[160:163], v[190:193], v[104:107]
	v_mfma_f32_16x16x32_bf16 v[84:87], v[152:155], v[198:201], v[84:87]
	v_mfma_f32_16x16x32_bf16 v[80:83], v[160:163], v[198:201], v[80:83]
	v_mfma_f32_16x16x32_bf16 v[68:71], v[152:155], v[206:209], v[68:71]
	v_mfma_f32_16x16x32_bf16 v[64:67], v[160:163], v[206:209], v[64:67]
	v_mfma_f32_16x16x32_bf16 v[124:127], v[156:159], v[186:189], v[124:127]
	v_mfma_f32_16x16x32_bf16 v[120:123], v[176:179], v[186:189], v[120:123]
	v_mfma_f32_16x16x32_bf16 v[108:111], v[156:159], v[194:197], v[108:111]
	v_mfma_f32_16x16x32_bf16 v[102:105], v[176:179], v[194:197], v[102:105]
	v_mfma_f32_16x16x32_bf16 v[84:87], v[156:159], v[202:205], v[84:87]
	v_mfma_f32_16x16x32_bf16 v[80:83], v[176:179], v[202:205], v[80:83]
	v_mfma_f32_16x16x32_bf16 v[68:71], v[156:159], v[210:213], v[68:71]
	v_mfma_f32_16x16x32_bf16 v[64:67], v[176:179], v[210:213], v[64:67]
	s_setprio 0
	s_barrier
	s_add_i32 s2, vcc_hi, s29
	v_lshl_add_u64 v[98:99], s[20:21], 0, v[166:167]
	s_mov_b32 m0, s2
	ds_read_b128 v[180:183], v231 offset:16384
	ds_read_b128 v[186:189], v231 offset:17408
	ds_read_b128 v[190:193], v231 offset:18432
	ds_read_b128 v[194:197], v231 offset:19456
	ds_read_b128 v[198:201], v231 offset:20480
	ds_read_b128 v[202:205], v231 offset:21504
	ds_read_b128 v[206:209], v231 offset:22528
	ds_read_b128 v[210:213], v231 offset:23552
	global_load_lds_dwordx4 v[98:99], off
	s_add_i32 m0, s2, 0x2000
	s_add_u32 s2, s20, 0x80000
	v_lshl_add_u64 v[184:185], s[20:21], 0, v[170:171]
	s_addc_u32 s3, s21, 0
	s_add_i32 s91, s91, s29
	global_load_lds_dwordx4 v[184:185], off
	s_mov_b32 m0, s91
	v_lshl_add_u64 v[214:215], s[22:23], 0, v[164:165]
	global_load_lds_dwordx4 v166, s[2:3]
	s_add_i32 m0, s91, 0x2000
	v_lshl_add_u64 v[220:221], s[22:23], 0, v[168:169]
	global_load_lds_dwordx4 v170, s[2:3]
	s_mov_b32 m0, s82
	s_nop 0
	global_load_lds_dwordx4 v[214:215], off
	s_mov_b32 m0, s50
	s_nop 0
	global_load_lds_dwordx4 v[220:221], off
	s_waitcnt vmcnt(8)
	s_waitcnt lgkmcnt(0)
	s_barrier
; #define PG8_STAGE(bufoff, gbase, voff) do { _Pragma("unroll") for (int _i = 0; _i < 2; ++_i) \
;         __builtin_amdgcn_global_load_lds((const unsigned*)((const char*)(gbase) + (voff)[_i]), (LAS unsigned*)(lds + (bufoff) + ldsw + _i * 8192), 16, 0, 0); } while (0)
; #define PG8_LDA(dst, b, h) do { _Pragma("unroll") for (int m = 0; m < 4; ++m) _Pragma("unroll") for (int k = 0; k < 2; ++k) dst[m][k] = *(const LAS bf16x8*)(lds + PG8_SA(b, h) + aoff + m * 2048 + k * 1024); } while (0)
; #define PG8_LDB(dst, b, h) do { _Pragma("unroll") for (int n = 0; n < 2; ++n) _Pragma("unroll") for (int k = 0; k < 2; ++k) dst[n][k] = *(const LAS bf16x8*)(lds + PG8_SB(b, h) + boff + n * 2048 + k * 1024); } while (0)
; #define PG8_MMA(ai, bj, At, Bt) do { __builtin_amdgcn_s_setprio(1); _Pragma("unroll") for (int m = 0; m < 4; ++m) _Pragma("unroll") for (int n = 0; n < 2; ++n) _Pragma("unroll") for (int k = 0; k < 2; ++k) \
;         acc[ai][bj][m][n] = __builtin_amdgcn_mfma_f32_16x16x32_bf16(Bt[n][k], At[m][k], acc[ai][bj][m][n], 0, 0, 0); __builtin_amdgcn_s_setprio(0); } while (0)
; #define PG8_WAIT_V(n) asm volatile("s_waitcnt vmcnt(" #n ")" ::: "memory")
; #define PG8_WAIT_L(n) asm volatile("s_waitcnt lgkmcnt(" #n ")" ::: "memory")
; #define PG8_BAR __builtin_amdgcn_s_barrier()
; #define PG8_SCHED __builtin_amdgcn_sched_barrier(0)
; template <class Epi, bool ALIGN_EPI, bool SP2>
; __device__ __forceinline__ void gemm_phase(LAS unsigned char* lds, const Gemm g, const Sched& S, const Epi& E) {
;     ...
;             PG8_WAIT_V(8); PG8_WAIT_L(0); PG8_BAR; PG8_MMA(1, 0, At, B0); PG8_MMA(1, 1, At, B1); PG8_BAR; PG8_SCHED;
;             PG8_LDB(B0, 1, 0); PG8_LDB(B1, 1, 1); PG8_SCHED; PG8_LDA(At, 1, 0); PG8_STAGE(PG8_SA(0, 1), a2 + hstep, voffA);
;             PG8_WAIT_V(8); PG8_WAIT_L(0); PG8_BAR; PG8_MMA(0, 0, At, B0); PG8_MMA(0, 1, At, B1); PG8_BAR; PG8_SCHED;
	s_setprio 1
	s_waitcnt lgkmcnt(0)
	v_mfma_f32_16x16x32_bf16 v[60:63], v[136:139], v[180:183], v[60:63]
	v_mfma_f32_16x16x32_bf16 v[56:59], v[144:147], v[180:183], v[56:59]
	v_mfma_f32_16x16x32_bf16 v[44:47], v[136:139], v[190:193], v[44:47]
	v_mfma_f32_16x16x32_bf16 v[40:43], v[144:147], v[190:193], v[40:43]
	v_mfma_f32_16x16x32_bf16 v[28:31], v[136:139], v[198:201], v[28:31]
	v_mfma_f32_16x16x32_bf16 v[24:27], v[144:147], v[198:201], v[24:27]
	v_mfma_f32_16x16x32_bf16 v[12:15], v[136:139], v[206:209], v[12:15]
	v_mfma_f32_16x16x32_bf16 v[8:11], v[144:147], v[206:209], v[8:11]
	v_mfma_f32_16x16x32_bf16 v[60:63], v[140:143], v[186:189], v[60:63]
	v_mfma_f32_16x16x32_bf16 v[56:59], v[148:151], v[186:189], v[56:59]
	v_mfma_f32_16x16x32_bf16 v[44:47], v[140:143], v[194:197], v[44:47]
	v_mfma_f32_16x16x32_bf16 v[40:43], v[148:151], v[194:197], v[40:43]
	v_mfma_f32_16x16x32_bf16 v[28:31], v[140:143], v[202:205], v[28:31]
	v_mfma_f32_16x16x32_bf16 v[24:27], v[148:151], v[202:205], v[24:27]
	v_mfma_f32_16x16x32_bf16 v[12:15], v[140:143], v[210:213], v[12:15]
	v_mfma_f32_16x16x32_bf16 v[8:11], v[148:151], v[210:213], v[8:11]
	s_setprio 0
	s_setprio 1
	v_mfma_f32_16x16x32_bf16 v[52:55], v[152:155], v[180:183], v[52:55]
	v_mfma_f32_16x16x32_bf16 v[48:51], v[160:163], v[180:183], v[48:51]
	v_mfma_f32_16x16x32_bf16 v[36:39], v[152:155], v[190:193], v[36:39]
	v_mfma_f32_16x16x32_bf16 v[32:35], v[160:163], v[190:193], v[32:35]
	v_mfma_f32_16x16x32_bf16 v[20:23], v[152:155], v[198:201], v[20:23]
	v_mfma_f32_16x16x32_bf16 v[16:19], v[160:163], v[198:201], v[16:19]
	v_mfma_f32_16x16x32_bf16 v[4:7], v[152:155], v[206:209], v[4:7]
	v_mfma_f32_16x16x32_bf16 v[0:3], v[160:163], v[206:209], v[0:3]
	v_mfma_f32_16x16x32_bf16 v[52:55], v[156:159], v[186:189], v[52:55]
	v_mfma_f32_16x16x32_bf16 v[48:51], v[176:179], v[186:189], v[48:51]
	v_mfma_f32_16x16x32_bf16 v[36:39], v[156:159], v[194:197], v[36:39]
	v_mfma_f32_16x16x32_bf16 v[32:35], v[176:179], v[194:197], v[32:35]
	v_mfma_f32_16x16x32_bf16 v[20:23], v[156:159], v[202:205], v[20:23]
	v_mfma_f32_16x16x32_bf16 v[16:19], v[176:179], v[202:205], v[16:19]
	v_mfma_f32_16x16x32_bf16 v[4:7], v[156:159], v[210:213], v[4:7]
	v_mfma_f32_16x16x32_bf16 v[0:3], v[176:179], v[210:213], v[0:3]
	s_setprio 0
	s_barrier
	s_add_i32 s91, 0, 0x18000
	v_add_u32_e32 v96, s91, v230
	s_add_i32 vcc_hi, 0, 0x1c000
	ds_read_b128 v[136:139], v96
	ds_read_b128 v[140:143], v96 offset:1024
	ds_read_b128 v[144:147], v96 offset:2048
	ds_read_b128 v[148:151], v96 offset:3072
	v_add_u32_e32 v96, vcc_hi, v230
	ds_read_b128 v[152:155], v96
	ds_read_b128 v[156:159], v96 offset:1024
	ds_read_b128 v[160:163], v96 offset:2048
	ds_read_b128 v[176:179], v96 offset:3072
	s_add_u32 s2, s22, 0x80000
	s_addc_u32 s3, s23, 0
	s_mov_b32 m0, s51
	ds_read_b128 v[180:183], v231 offset:32768
	ds_read_b128 v[186:189], v231 offset:33792
	ds_read_b128 v[190:193], v231 offset:34816
	ds_read_b128 v[194:197], v231 offset:35840
	ds_read_b128 v[198:201], v231 offset:36864
	ds_read_b128 v[202:205], v231 offset:37888
	ds_read_b128 v[206:209], v231 offset:38912
	ds_read_b128 v[210:213], v231 offset:39936
	global_load_lds_dwordx4 v164, s[2:3]
	v_lshl_add_u64 v[106:107], s[2:3], 0, v[168:169]
	s_mov_b32 m0, s76
	s_nop 0
	global_load_lds_dwordx4 v[106:107], off
	s_waitcnt vmcnt(8)
	s_waitcnt lgkmcnt(0)
	s_barrier
	s_setprio 1
	s_waitcnt lgkmcnt(0)
	v_mfma_f32_16x16x32_bf16 v[132:135], v[136:139], v[180:183], v[132:135]
	v_mfma_f32_16x16x32_bf16 v[128:131], v[144:147], v[180:183], v[128:131]
	v_mfma_f32_16x16x32_bf16 v[116:119], v[136:139], v[190:193], v[116:119]
	v_mfma_f32_16x16x32_bf16 v[112:115], v[144:147], v[190:193], v[112:115]
	v_mfma_f32_16x16x32_bf16 v[92:95], v[136:139], v[198:201], v[92:95]
	v_mfma_f32_16x16x32_bf16 v[88:91], v[144:147], v[198:201], v[88:91]
	v_mfma_f32_16x16x32_bf16 v[76:79], v[136:139], v[206:209], v[76:79]
	v_mfma_f32_16x16x32_bf16 v[72:75], v[144:147], v[206:209], v[72:75]
	v_mfma_f32_16x16x32_bf16 v[132:135], v[140:143], v[186:189], v[132:135]
	v_mfma_f32_16x16x32_bf16 v[128:131], v[148:151], v[186:189], v[128:131]
	v_mfma_f32_16x16x32_bf16 v[116:119], v[140:143], v[194:197], v[116:119]
	v_mfma_f32_16x16x32_bf16 v[112:115], v[148:151], v[194:197], v[112:115]
	v_mfma_f32_16x16x32_bf16 v[92:95], v[140:143], v[202:205], v[92:95]
	v_mfma_f32_16x16x32_bf16 v[88:91], v[148:151], v[202:205], v[88:91]
	v_mfma_f32_16x16x32_bf16 v[76:79], v[140:143], v[210:213], v[76:79]
	v_mfma_f32_16x16x32_bf16 v[72:75], v[148:151], v[210:213], v[72:75]
	s_setprio 0
	s_setprio 1
	v_mfma_f32_16x16x32_bf16 v[124:127], v[152:155], v[180:183], v[124:127]
	v_mfma_f32_16x16x32_bf16 v[120:123], v[160:163], v[180:183], v[120:123]
	v_mfma_f32_16x16x32_bf16 v[106:109], v[152:155], v[190:193], v[108:111]
	v_mfma_f32_16x16x32_bf16 v[102:105], v[160:163], v[190:193], v[102:105]
	v_mfma_f32_16x16x32_bf16 v[84:87], v[152:155], v[198:201], v[84:87]
	v_mfma_f32_16x16x32_bf16 v[80:83], v[160:163], v[198:201], v[80:83]
	v_mfma_f32_16x16x32_bf16 v[68:71], v[152:155], v[206:209], v[68:71]
	v_mfma_f32_16x16x32_bf16 v[64:67], v[160:163], v[206:209], v[64:67]
	v_mfma_f32_16x16x32_bf16 v[124:127], v[156:159], v[186:189], v[124:127]
	v_mfma_f32_16x16x32_bf16 v[120:123], v[176:179], v[186:189], v[120:123]
	v_mfma_f32_16x16x32_bf16 v[108:111], v[156:159], v[194:197], v[106:109]
	v_mfma_f32_16x16x32_bf16 v[104:107], v[176:179], v[194:197], v[102:105]
	v_mfma_f32_16x16x32_bf16 v[84:87], v[156:159], v[202:205], v[84:87]
	v_mfma_f32_16x16x32_bf16 v[80:83], v[176:179], v[202:205], v[80:83]
	v_mfma_f32_16x16x32_bf16 v[68:71], v[156:159], v[210:213], v[68:71]
	v_mfma_f32_16x16x32_bf16 v[64:67], v[176:179], v[210:213], v[64:67]
	s_setprio 0
	s_barrier
; #define PG8_STAGE(bufoff, gbase, voff) do { _Pragma("unroll") for (int _i = 0; _i < 2; ++_i) \
;         __builtin_amdgcn_global_load_lds((const unsigned*)((const char*)(gbase) + (voff)[_i]), (LAS unsigned*)(lds + (bufoff) + ldsw + _i * 8192), 16, 0, 0); } while (0)
; #define PG8_LDA(dst, b, h) do { _Pragma("unroll") for (int m = 0; m < 4; ++m) _Pragma("unroll") for (int k = 0; k < 2; ++k) dst[m][k] = *(const LAS bf16x8*)(lds + PG8_SA(b, h) + aoff + m * 2048 + k * 1024); } while (0)
; #define PG8_MMA(ai, bj, At, Bt) do { __builtin_amdgcn_s_setprio(1); _Pragma("unroll") for (int m = 0; m < 4; ++m) _Pragma("unroll") for (int n = 0; n < 2; ++n) _Pragma("unroll") for (int k = 0; k < 2; ++k) \
;         acc[ai][bj][m][n] = __builtin_amdgcn_mfma_f32_16x16x32_bf16(Bt[n][k], At[m][k], acc[ai][bj][m][n], 0, 0, 0); __builtin_amdgcn_s_setprio(0); } while (0)
; #define PG8_WAIT_V(n) asm volatile("s_waitcnt vmcnt(" #n ")" ::: "memory")
; #define PG8_WAIT_L(n) asm volatile("s_waitcnt lgkmcnt(" #n ")" ::: "memory")
; #define PG8_BAR __builtin_amdgcn_s_barrier()
; #define PG8_SCHED __builtin_amdgcn_sched_barrier(0)
; template <class Epi, bool ALIGN_EPI, bool SP2>
; __device__ __forceinline__ void gemm_phase(LAS unsigned char* lds, const Gemm g, const Sched& S, const Epi& E) {
;     ...
;             PG8_LDA(At, 1, 1); PG8_STAGE(PG8_SB(1, 0), b3, voffB); PG8_STAGE(PG8_SB(1, 1), b3 + hstep, voffB); PG8_STAGE(PG8_SA(1, 0), a3, voffA);
;             PG8_WAIT_V(8); PG8_WAIT_L(0); PG8_BAR; PG8_MMA(1, 0, At, B0); PG8_MMA(1, 1, At, B1); PG8_BAR; PG8_SCHED;
	s_add_i32 s2, s91, s29
	v_lshl_add_u64 v[98:99], v[98:99], 0, s[94:95]
	s_mov_b32 m0, s2
	ds_read_b128 v[180:183], v231 offset:49152
	ds_read_b128 v[186:189], v231 offset:50176
	ds_read_b128 v[190:193], v231 offset:51200
	ds_read_b128 v[194:197], v231 offset:52224
	ds_read_b128 v[198:201], v231 offset:53248
	ds_read_b128 v[202:205], v231 offset:54272
	ds_read_b128 v[206:209], v231 offset:55296
	ds_read_b128 v[210:213], v231 offset:56320
	global_load_lds_dwordx4 v[98:99], off
	s_add_i32 m0, s2, 0x2000
	s_add_u32 s2, s20, 0x80080
	v_lshl_add_u64 v[98:99], v[184:185], 0, s[94:95]
	s_addc_u32 s3, s21, 0
	s_add_i32 s20, vcc_hi, s29
	global_load_lds_dwordx4 v[98:99], off
	s_mov_b32 m0, s20
	s_nop 0
	global_load_lds_dwordx4 v166, s[2:3]
	s_add_i32 m0, s20, 0x2000
	s_nop 0
	global_load_lds_dwordx4 v170, s[2:3]
	v_lshl_add_u64 v[98:99], v[214:215], 0, s[94:95]
	s_mov_b32 m0, s97
	s_nop 0
	global_load_lds_dwordx4 v[98:99], off
	v_lshl_add_u64 v[98:99], v[220:221], 0, s[94:95]
	s_mov_b32 m0, s35
	s_nop 0
	global_load_lds_dwordx4 v[98:99], off
	s_waitcnt vmcnt(8)
	s_waitcnt lgkmcnt(0)
	s_barrier
	s_setprio 1
	s_waitcnt lgkmcnt(0)
	v_mfma_f32_16x16x32_bf16 v[60:63], v[136:139], v[180:183], v[60:63]
	v_mfma_f32_16x16x32_bf16 v[56:59], v[144:147], v[180:183], v[56:59]
	v_mfma_f32_16x16x32_bf16 v[44:47], v[136:139], v[190:193], v[44:47]
	v_mfma_f32_16x16x32_bf16 v[40:43], v[144:147], v[190:193], v[40:43]
	v_mfma_f32_16x16x32_bf16 v[28:31], v[136:139], v[198:201], v[28:31]
	v_mfma_f32_16x16x32_bf16 v[24:27], v[144:147], v[198:201], v[24:27]
	v_mfma_f32_16x16x32_bf16 v[12:15], v[136:139], v[206:209], v[12:15]
	v_mfma_f32_16x16x32_bf16 v[8:11], v[144:147], v[206:209], v[8:11]
	v_mfma_f32_16x16x32_bf16 v[60:63], v[140:143], v[186:189], v[60:63]
	v_mfma_f32_16x16x32_bf16 v[56:59], v[148:151], v[186:189], v[56:59]
	v_mfma_f32_16x16x32_bf16 v[44:47], v[140:143], v[194:197], v[44:47]
	v_mfma_f32_16x16x32_bf16 v[40:43], v[148:151], v[194:197], v[40:43]
	v_mfma_f32_16x16x32_bf16 v[28:31], v[140:143], v[202:205], v[28:31]
	v_mfma_f32_16x16x32_bf16 v[24:27], v[148:151], v[202:205], v[24:27]
	v_mfma_f32_16x16x32_bf16 v[12:15], v[140:143], v[210:213], v[12:15]
	v_mfma_f32_16x16x32_bf16 v[8:11], v[148:151], v[210:213], v[8:11]
	s_setprio 0
	s_setprio 1
	v_mfma_f32_16x16x32_bf16 v[52:55], v[152:155], v[180:183], v[52:55]
	v_mfma_f32_16x16x32_bf16 v[48:51], v[160:163], v[180:183], v[48:51]
	v_mfma_f32_16x16x32_bf16 v[36:39], v[152:155], v[190:193], v[36:39]
	v_mfma_f32_16x16x32_bf16 v[32:35], v[160:163], v[190:193], v[32:35]
	v_mfma_f32_16x16x32_bf16 v[20:23], v[152:155], v[198:201], v[20:23]
	v_mfma_f32_16x16x32_bf16 v[16:19], v[160:163], v[198:201], v[16:19]
	v_mfma_f32_16x16x32_bf16 v[4:7], v[152:155], v[206:209], v[4:7]
	v_mfma_f32_16x16x32_bf16 v[0:3], v[160:163], v[206:209], v[0:3]
	v_mfma_f32_16x16x32_bf16 v[52:55], v[156:159], v[186:189], v[52:55]
	v_mfma_f32_16x16x32_bf16 v[48:51], v[176:179], v[186:189], v[48:51]
	v_mfma_f32_16x16x32_bf16 v[36:39], v[156:159], v[194:197], v[36:39]
	v_mfma_f32_16x16x32_bf16 v[32:35], v[176:179], v[194:197], v[32:35]
	v_mfma_f32_16x16x32_bf16 v[20:23], v[156:159], v[202:205], v[20:23]
	v_mfma_f32_16x16x32_bf16 v[16:19], v[176:179], v[202:205], v[16:19]
	v_mfma_f32_16x16x32_bf16 v[4:7], v[156:159], v[210:213], v[4:7]
	v_mfma_f32_16x16x32_bf16 v[0:3], v[176:179], v[210:213], v[0:3]
	s_setprio 0
	s_barrier
	s_add_u32 s44, s44, 0x100
	s_addc_u32 s45, s45, 0
	s_add_u32 s24, s24, 0x100
	s_addc_u32 s25, s25, 0
	s_cmp_ge_i32 vcc_lo, s36
	s_mov_b32 s20, vcc_lo
	s_cbranch_scc0 .LBB0_585
	s_mov_b32 s91, 0x12000
	s_and_b64 vcc, exec, s[60:61]
	s_cbranch_vccz .LBB0_588
